# P0 keeps only list-0 items below 12288 and rebalances them between GEMV and non-GEMV waves; the other 12288 weight-transpose items are converted by waves 1-7 inside grid-barrier waits of seams 2-8
# speedup vs baseline: 1.0136x; 1.0136x over previous
.LBB0_117:
	v_add_u32_e32 v40, s26, v68
	v_ashrrev_i32_e32 v38, 8, v40
	v_ashrrev_i32_e32 v39, 31, v38
	s_ashr_i32 s75, s74, 31
	v_lshlrev_b64 v[38:39], 20, v[38:39]
	s_waitcnt vmcnt(10)
	v_cvt_pk_bf16_f32 v34, v2, v6
	s_lshl_b64 s[24:25], s[74:75], 15
	v_lshl_add_u64 v[38:39], s[14:15], 0, v[38:39]
	v_lshlrev_b32_e32 v2, 7, v40
	v_lshl_add_u64 v[38:39], v[38:39], 0, s[24:25]
	v_and_b32_e32 v70, 0x7f80, v2
	v_lshl_add_u64 v[38:39], v[38:39], 0, v[70:71]
	v_mov_b32_e32 v75, v71
	v_add_u32_e32 v6, s26, v67
	s_waitcnt vmcnt(8)
	v_cvt_pk_bf16_f32 v35, v10, v14
	s_waitcnt vmcnt(6)
	v_cvt_pk_bf16_f32 v36, v18, v22
	s_waitcnt vmcnt(4)
	v_cvt_pk_bf16_f32 v37, v26, v30
	v_lshl_add_u64 v[38:39], v[38:39], 0, v[74:75]
	v_ashrrev_i32_e32 v2, 8, v6
	global_store_dwordx4 v[38:39], v[34:37], off
	v_lshlrev_b32_e32 v6, 7, v6
	v_and_b32_e32 v70, 0x7f80, v6
	v_cvt_pk_bf16_f32 v34, v3, v7
	v_ashrrev_i32_e32 v3, 31, v2
	v_lshlrev_b64 v[2:3], 20, v[2:3]
	v_lshl_add_u64 v[2:3], s[14:15], 0, v[2:3]
	v_lshl_add_u64 v[2:3], v[2:3], 0, s[24:25]
	v_lshl_add_u64 v[2:3], v[2:3], 0, v[70:71]
	v_cvt_pk_bf16_f32 v35, v11, v15
	v_cvt_pk_bf16_f32 v36, v19, v23
	v_cvt_pk_bf16_f32 v37, v27, v31
	v_lshl_add_u64 v[2:3], v[2:3], 0, v[74:75]
	v_add_u32_e32 v6, s26, v69
	global_store_dwordx4 v[2:3], v[34:37], off
	v_ashrrev_i32_e32 v2, 8, v6
	v_ashrrev_i32_e32 v3, 31, v2
	v_cvt_pk_bf16_f32 v34, v4, v8
	v_add_u32_e32 v8, s26, v76
	v_lshlrev_b32_e32 v4, 7, v6
	v_ashrrev_i32_e32 v6, 8, v8
	v_lshlrev_b64 v[2:3], 20, v[2:3]
	v_ashrrev_i32_e32 v7, 31, v6
	v_lshl_add_u64 v[2:3], s[14:15], 0, v[2:3]
	v_lshlrev_b64 v[6:7], 20, v[6:7]
	v_lshl_add_u64 v[2:3], v[2:3], 0, s[24:25]
	v_and_b32_e32 v70, 0x7f80, v4
	v_lshl_add_u64 v[6:7], s[14:15], 0, v[6:7]
	v_lshlrev_b32_e32 v8, 7, v8
	v_lshl_add_u64 v[2:3], v[2:3], 0, v[70:71]
	v_lshl_add_u64 v[6:7], v[6:7], 0, s[24:25]
	v_and_b32_e32 v70, 0x7f80, v8
	v_cvt_pk_bf16_f32 v35, v12, v16
	v_cvt_pk_bf16_f32 v36, v20, v24
	v_cvt_pk_bf16_f32 v37, v28, v32
	v_lshl_add_u64 v[2:3], v[2:3], 0, v[74:75]
	v_lshl_add_u64 v[6:7], v[6:7], 0, v[70:71]
	s_add_i32 s12, s28, 0x1000
	s_add_i32 s27, s28, 0x1800
	global_store_dwordx4 v[2:3], v[34:37], off
	v_cvt_pk_bf16_f32 v2, v5, v9
	v_cvt_pk_bf16_f32 v3, v13, v17
	v_cvt_pk_bf16_f32 v4, v21, v25
	v_cvt_pk_bf16_f32 v5, v29, v33
	v_lshl_add_u64 v[6:7], v[6:7], 0, v[74:75]
	s_cmpk_lt_i32 s28, 0x2000
	global_store_dwordx4 v[6:7], v[2:5], off
	s_cbranch_scc0 .LBB0_119
	s_cmpk_lt_i32 s70, 0x480
	s_cbranch_scc1 .LBB0_119
	s_mov_b32 s28, s12
	s_branch .LBB0_88
.LBB0_119:
	s_cmpk_lt_i32 s70, 0x480
	s_cbranch_scc1 .Lmy_p0x_done
	s_sub_i32 s34, s70, 0x480
.Lmy_p0x_loop:
	s_mov_b32 s35, s34
	s_movk_i32 s33, 0x1000
	s_cmpk_lt_u32 s35, 0x480
	s_cbranch_scc1 .Lmy_p0x_it
	s_sub_u32 s35, s35, 0x480
	s_addk_i32 s33, 0x800
	s_cmpk_lt_u32 s35, 0x480
	s_cbranch_scc1 .Lmy_p0x_it
	s_sub_u32 s35, s35, 0x480
	s_addk_i32 s33, 0x800
	s_cmpk_lt_u32 s35, 0x480
	s_cbranch_scc1 .Lmy_p0x_it
	s_sub_u32 s35, s35, 0x480
	s_addk_i32 s33, 0x800
.Lmy_p0x_it:
	s_add_u32 s6, s35, s33
	v_and_b32_e32 v1, 63, v0
	v_readlane_b32 s10, v254, 2
	v_readlane_b32 s11, v254, 3
	s_sub_u32 s10, s10, 0xc8
	s_subb_u32 s11, s11, 0
	s_cmp_lt_u32 s6, 0x1600
	s_cbranch_scc1 .Lmy_cvp0x_g1
	s_cmp_lt_u32 s6, 0x2c00
	s_cbranch_scc1 .Lmy_cvp0x_u1
	s_cmp_lt_u32 s6, 0x3400
	s_cbranch_scc1 .Lmy_cvp0x_wo
	s_cmp_lt_u32 s6, 0x4a00
	s_cbranch_scc1 .Lmy_cvp0x_g2
	s_load_dwordx2 s[12:13], s[10:11], 0xa0
	s_sub_u32 s6, s6, 0x4a00
	s_movk_i32 s14, 0x80
	s_mov_b32 s20, 0x6a00000
	s_branch .Lmy_cvp0x_gu
.Lmy_cvp0x_g2:
	s_load_dwordx2 s[12:13], s[10:11], 0x98
	s_sub_u32 s6, s6, 0x3400
	s_mov_b32 s14, 0
	s_mov_b32 s20, 0x6a00000
	s_branch .Lmy_cvp0x_gu
.Lmy_cvp0x_u1:
	s_load_dwordx2 s[12:13], s[10:11], 0x30
	s_sub_u32 s6, s6, 0x1600
	s_movk_i32 s14, 0x80
	s_mov_b32 s20, 0x800000
	s_branch .Lmy_cvp0x_gu
.Lmy_cvp0x_g1:
	s_load_dwordx2 s[12:13], s[10:11], 0x28
	s_mov_b32 s14, 0
	s_mov_b32 s20, 0x800000
.Lmy_cvp0x_gu:
	s_mul_i32 s15, s6, 0x1746
	s_lshr_b32 s15, s15, 20
	s_mul_i32 s30, s15, 0xb0
	s_sub_u32 s30, s6, s30
	s_lshl_b32 s31, s30, 5
	s_lshr_b32 s18, s31, 7
	s_lshl_b32 s18, s18, 8
	s_and_b32 s19, s31, 0x7f
	s_add_u32 s18, s18, s19
	s_add_u32 s18, s18, s14
	s_movk_i32 s19, 0x1600
	s_branch .Lmy_cvp0x_go
.Lmy_cvp0x_wo:
	s_load_dwordx2 s[12:13], s[10:11], 0x88
	s_sub_u32 s6, s6, 0x2c00
	s_lshr_b32 s15, s6, 6
	s_and_b32 s30, s6, 63
	s_lshl_b32 s31, s30, 5
	s_mov_b32 s18, s31
	s_movk_i32 s19, 0x800
	s_mov_b32 s20, 0x6200000
.Lmy_cvp0x_go:
	s_add_u32 s20, s50, s20
	s_addc_u32 s21, s51, 0
	v_and_b32_e32 v2, 7, v1
	v_lshrrev_b32_e32 v3, 3, v1
	s_lshl_b32 s24, s15, 6
	v_lshl_add_u32 v4, v2, 3, s24
	v_mul_lo_u32 v4, v4, s19
	v_lshl_add_u32 v5, v3, 2, s31
	v_add_u32_e32 v4, v4, v5
	v_mov_b32_e32 v5, 0
	v_lshlrev_b64 v[4:5], 2, v[4:5]
	s_lshl_b32 s26, s19, 2
	s_mov_b32 s27, 0
	s_lshr_b32 s28, s18, 8
	s_and_b32 s29, s18, 0xff
	s_lshl_b32 s28, s28, 5
	s_add_u32 s28, s28, s15
	s_lshl_b32 s28, s28, 8
	s_add_u32 s28, s28, s29
	s_waitcnt lgkmcnt(0)
	v_lshl_add_u64 v[4:5], s[12:13], 0, v[4:5]
	global_load_dwordx4 v[8:11], v[4:5], off nt
	v_lshl_add_u64 v[4:5], v[4:5], 0, s[26:27]
	global_load_dwordx4 v[12:15], v[4:5], off nt
	v_lshl_add_u64 v[4:5], v[4:5], 0, s[26:27]
	global_load_dwordx4 v[16:19], v[4:5], off nt
	v_lshl_add_u64 v[4:5], v[4:5], 0, s[26:27]
	global_load_dwordx4 v[20:23], v[4:5], off nt
	v_lshl_add_u64 v[4:5], v[4:5], 0, s[26:27]
	global_load_dwordx4 v[24:27], v[4:5], off nt
	v_lshl_add_u64 v[4:5], v[4:5], 0, s[26:27]
	global_load_dwordx4 v[28:31], v[4:5], off nt
	v_lshl_add_u64 v[4:5], v[4:5], 0, s[26:27]
	global_load_dwordx4 v[32:35], v[4:5], off nt
	v_lshl_add_u64 v[4:5], v[4:5], 0, s[26:27]
	global_load_dwordx4 v[36:39], v[4:5], off nt
	v_lshl_add_u32 v6, v3, 2, s28
	v_lshlrev_b32_e32 v6, 7, v6
	v_lshl_add_u32 v6, v2, 4, v6
	v_mov_b32_e32 v7, 0
	v_lshl_add_u64 v[6:7], s[20:21], 0, v[6:7]
	s_addk_i32 s34, 0x380
	s_cmpk_lt_u32 s34, 0x1200
	s_cbranch_scc0 .Lmy_p0x_single
	s_mov_b32 s35, s34
	s_movk_i32 s33, 0x1000
	s_cmpk_lt_u32 s35, 0x480
	s_cbranch_scc1 .Lmy_p0x_it2
	s_sub_u32 s35, s35, 0x480
	s_addk_i32 s33, 0x800
	s_cmpk_lt_u32 s35, 0x480
	s_cbranch_scc1 .Lmy_p0x_it2
	s_sub_u32 s35, s35, 0x480
	s_addk_i32 s33, 0x800
	s_cmpk_lt_u32 s35, 0x480
	s_cbranch_scc1 .Lmy_p0x_it2
	s_sub_u32 s35, s35, 0x480
	s_addk_i32 s33, 0x800

.Lmy_cvp0y_go:
	s_add_u32 s20, s50, s20
	s_addc_u32 s21, s51, 0
	v_and_b32_e32 v2, 7, v1
	v_lshrrev_b32_e32 v3, 3, v1
	s_lshl_b32 s24, s15, 6
	v_lshl_add_u32 v4, v2, 3, s24
	v_mul_lo_u32 v4, v4, s19
	v_lshl_add_u32 v5, v3, 2, s31
	v_add_u32_e32 v4, v4, v5
	v_mov_b32_e32 v5, 0
	v_lshlrev_b64 v[4:5], 2, v[4:5]
	s_lshl_b32 s26, s19, 2
	s_mov_b32 s27, 0
	s_lshr_b32 s28, s18, 8
	s_and_b32 s29, s18, 0xff
	s_lshl_b32 s28, s28, 5
	s_add_u32 s28, s28, s15
	s_lshl_b32 s28, s28, 8
	s_add_u32 s28, s28, s29
	s_waitcnt lgkmcnt(0)
	v_lshl_add_u64 v[4:5], s[12:13], 0, v[4:5]
	global_load_dwordx4 v[64:67], v[4:5], off nt
	v_lshl_add_u64 v[4:5], v[4:5], 0, s[26:27]
	global_load_dwordx4 v[68:71], v[4:5], off nt
	v_lshl_add_u64 v[4:5], v[4:5], 0, s[26:27]
	global_load_dwordx4 v[72:75], v[4:5], off nt
	v_lshl_add_u64 v[4:5], v[4:5], 0, s[26:27]
	global_load_dwordx4 v[76:79], v[4:5], off nt
	v_lshl_add_u64 v[4:5], v[4:5], 0, s[26:27]
	global_load_dwordx4 v[80:83], v[4:5], off nt
	v_lshl_add_u64 v[4:5], v[4:5], 0, s[26:27]
	global_load_dwordx4 v[84:87], v[4:5], off nt
	v_lshl_add_u64 v[4:5], v[4:5], 0, s[26:27]
	global_load_dwordx4 v[88:91], v[4:5], off nt
	v_lshl_add_u64 v[4:5], v[4:5], 0, s[26:27]
	global_load_dwordx4 v[92:95], v[4:5], off nt
	v_lshl_add_u32 v62, v3, 2, s28
	v_lshlrev_b32_e32 v62, 7, v62
	v_lshl_add_u32 v62, v2, 4, v62
	v_mov_b32_e32 v63, 0
	v_lshl_add_u64 v[62:63], s[20:21], 0, v[62:63]
	s_waitcnt vmcnt(8)
	v_cvt_pk_bf16_f32 v40, v8, v12
	v_cvt_pk_bf16_f32 v41, v16, v20
	v_cvt_pk_bf16_f32 v42, v24, v28
	v_cvt_pk_bf16_f32 v43, v32, v36
	global_store_dwordx4 v[6:7], v[40:43], off
	v_cvt_pk_bf16_f32 v44, v9, v13
	v_cvt_pk_bf16_f32 v45, v17, v21
	v_cvt_pk_bf16_f32 v46, v25, v29
	v_cvt_pk_bf16_f32 v47, v33, v37
	global_store_dwordx4 v[6:7], v[44:47], off offset:128
	v_cvt_pk_bf16_f32 v48, v10, v14
	v_cvt_pk_bf16_f32 v49, v18, v22
	v_cvt_pk_bf16_f32 v50, v26, v30
	v_cvt_pk_bf16_f32 v51, v34, v38
	global_store_dwordx4 v[6:7], v[48:51], off offset:256
	v_cvt_pk_bf16_f32 v52, v11, v15
	v_cvt_pk_bf16_f32 v53, v19, v23
	v_cvt_pk_bf16_f32 v54, v27, v31
	v_cvt_pk_bf16_f32 v55, v35, v39
	global_store_dwordx4 v[6:7], v[52:55], off offset:384
	s_waitcnt vmcnt(4)
	v_cvt_pk_bf16_f32 v96, v64, v68
	v_cvt_pk_bf16_f32 v97, v72, v76
	v_cvt_pk_bf16_f32 v98, v80, v84
	v_cvt_pk_bf16_f32 v99, v88, v92
	global_store_dwordx4 v[62:63], v[96:99], off
	v_cvt_pk_bf16_f32 v100, v65, v69
	v_cvt_pk_bf16_f32 v101, v73, v77
	v_cvt_pk_bf16_f32 v102, v81, v85
	v_cvt_pk_bf16_f32 v103, v89, v93
	global_store_dwordx4 v[62:63], v[100:103], off offset:128
	v_cvt_pk_bf16_f32 v104, v66, v70
	v_cvt_pk_bf16_f32 v105, v74, v78
	v_cvt_pk_bf16_f32 v106, v82, v86
	v_cvt_pk_bf16_f32 v107, v90, v94
	global_store_dwordx4 v[62:63], v[104:107], off offset:256
	v_cvt_pk_bf16_f32 v108, v67, v71
	v_cvt_pk_bf16_f32 v109, v75, v79
	v_cvt_pk_bf16_f32 v110, v83, v87
	v_cvt_pk_bf16_f32 v111, v91, v95
	global_store_dwordx4 v[62:63], v[108:111], off offset:384
	s_addk_i32 s34, 0x380
	s_cmpk_lt_u32 s34, 0x1200
	s_cbranch_scc1 .Lmy_p0x_loop
	s_branch .Lmy_p0x_done
.Lmy_p0x_single:
	s_waitcnt vmcnt(0)
	v_cvt_pk_bf16_f32 v40, v8, v12
	v_cvt_pk_bf16_f32 v41, v16, v20
	v_cvt_pk_bf16_f32 v42, v24, v28
	v_cvt_pk_bf16_f32 v43, v32, v36
	global_store_dwordx4 v[6:7], v[40:43], off
	v_cvt_pk_bf16_f32 v44, v9, v13
	v_cvt_pk_bf16_f32 v45, v17, v21
	v_cvt_pk_bf16_f32 v46, v25, v29
	v_cvt_pk_bf16_f32 v47, v33, v37
	global_store_dwordx4 v[6:7], v[44:47], off offset:128
	v_cvt_pk_bf16_f32 v48, v10, v14
	v_cvt_pk_bf16_f32 v49, v18, v22
	v_cvt_pk_bf16_f32 v50, v26, v30
	v_cvt_pk_bf16_f32 v51, v34, v38
	global_store_dwordx4 v[6:7], v[48:51], off offset:256
	v_cvt_pk_bf16_f32 v52, v11, v15
	v_cvt_pk_bf16_f32 v53, v19, v23
	v_cvt_pk_bf16_f32 v54, v27, v31
	v_cvt_pk_bf16_f32 v55, v35, v39
	global_store_dwordx4 v[6:7], v[52:55], off offset:384
.Lmy_p0x_done:
.LBB0_128:
	v_lshl_or_b32 v26, s70, 6, v1
	s_mov_b32 s0, 0x10000
	v_cmp_gt_i32_e32 vcc, s0, v26
	s_and_saveexec_b64 s[6:7], vcc
	s_cbranch_execz .LBB0_137
	s_waitcnt lgkmcnt(0)
	s_add_u32 s10, s50, 0x100000
	s_addc_u32 s11, s51, 0
	v_and_b32_e32 v2, 15, v0
	v_lshlrev_b32_e32 v2, 2, v2
	s_getpc_b64 s[0:1]
	s_add_u32 s0, s0, _ZL8ROPE_INV@rel32@lo+4
	s_addc_u32 s1, s1, _ZL8ROPE_INV@rel32@hi+12
	global_load_dword v27, v2, s[0:1]
	s_mov_b32 s14, 0x6dc9c883
	s_mov_b32 s18, 0x54442d18
	s_mov_b32 s20, 0x33145c07
	s_mov_b32 s24, 0xeff8d898
	v_mov_b32_e32 v12, 0x1a01a01a
	s_mov_b32 s26, 0x67f544e4
	v_mov_b32_e32 v22, 0x55555555
	s_lshl_b32 s28, s3, 9
	v_lshlrev_b32_e32 v8, 1, v26
	s_lshl_b32 s29, s3, 10
	s_mov_b64 s[12:13], 0
	s_mov_b32 s15, 0x3fe45f30
	s_mov_b32 s19, 0xbff921fb
	s_mov_b32 s21, 0xbc91a626
	v_mov_b32_e32 v10, 0xb7789f5c
	v_mov_b32_e32 v11, 0xbe927e4f
	s_mov_b32 s25, 0x3e21eed8
	v_mov_b32_e32 v13, 0x3efa01a0
	v_mov_b32_e32 v14, 0xa556c734
	v_mov_b32_e32 v15, 0x3ec71de3
	s_mov_b32 s27, 0xbe5ae645
	v_mov_b32_e32 v16, 0x16c16c17
	v_mov_b32_e32 v17, 0xbf56c16c
	v_mov_b32_e32 v19, 0xbf2a01a0
	v_mov_b32_e32 v18, v12
	v_mov_b32_e32 v20, 0x11111111
	v_mov_b32_e32 v21, 0x3f811111
	v_mov_b32_e32 v23, 0x3fa55555
	v_mov_b32_e32 v25, 0xbfc55555
	v_mov_b32_e32 v24, v22
	s_mov_b32 s30, 0xffff
	s_waitcnt vmcnt(0)
	s_branch .LBB0_132

.LBB0_355:
	s_or_b64 exec, exec, s[12:13]
	s_waitcnt vmcnt(0)
	s_branch .LBB0_356
.Lmy_cv2_entry:
	s_mov_b64 exec, -1
	s_cmpk_lg_i32 s3, 0x100
	s_cbranch_scc1 .Lmy_cv2_done
	v_readfirstlane_b32 s6, v0
	s_nop 0
	s_lshr_b32 s6, s6, 6
	s_mul_i32 s7, s2, 7
	s_add_i32 s6, s6, s7
	s_add_i32 s6, s6, 12287
	s_cmp_gt_u32 s6, 0x5fff
	s_cbranch_scc1 .Lmy_cv2_done
	v_and_b32_e32 v1, 63, v0
	v_readlane_b32 s10, v254, 2
	v_readlane_b32 s11, v254, 3
	s_sub_u32 s10, s10, 0xc8
	s_subb_u32 s11, s11, 0
	s_cmp_lt_u32 s6, 0x1600
	s_cbranch_scc1 .Lmy_cv2_g1
	s_cmp_lt_u32 s6, 0x2c00
	s_cbranch_scc1 .Lmy_cv2_u1
	s_cmp_lt_u32 s6, 0x3400
	s_cbranch_scc1 .Lmy_cv2_wo
	s_cmp_lt_u32 s6, 0x4a00
	s_cbranch_scc1 .Lmy_cv2_g2
	s_load_dwordx2 s[12:13], s[10:11], 0xa0
	s_sub_u32 s6, s6, 0x4a00
	s_movk_i32 s14, 0x80
	s_mov_b32 s20, 0x6a00000
	s_branch .Lmy_cv2_gu

.Lmy_cv2_gu:
	s_mul_i32 s15, s6, 0x1746
	s_lshr_b32 s15, s15, 20
	s_mul_i32 s16, s15, 0xb0
	s_sub_u32 s16, s6, s16
	s_lshl_b32 s17, s16, 5
	s_lshr_b32 s18, s17, 7
	s_lshl_b32 s18, s18, 8
	s_and_b32 s19, s17, 0x7f
	s_add_u32 s18, s18, s19
	s_add_u32 s18, s18, s14
	s_movk_i32 s19, 0x1600
	s_branch .Lmy_cv2_go
.Lmy_cv2_wo:
	s_load_dwordx2 s[12:13], s[10:11], 0x88
	s_sub_u32 s6, s6, 0x2c00
	s_lshr_b32 s15, s6, 6
	s_and_b32 s16, s6, 63
	s_lshl_b32 s17, s16, 5
	s_mov_b32 s18, s17
	s_movk_i32 s19, 0x800
	s_mov_b32 s20, 0x6200000
.Lmy_cv2_go:
	s_add_u32 s20, s50, s20
	s_addc_u32 s21, s51, 0
	v_and_b32_e32 v2, 7, v1
	v_lshrrev_b32_e32 v3, 3, v1
	s_lshl_b32 s24, s15, 6
	v_lshl_add_u32 v4, v2, 3, s24
	v_mul_lo_u32 v4, v4, s19
	v_lshl_add_u32 v5, v3, 2, s17
	v_add_u32_e32 v4, v4, v5
	v_mov_b32_e32 v5, 0
	v_lshlrev_b64 v[4:5], 2, v[4:5]
	s_lshl_b32 s26, s19, 2
	s_mov_b32 s27, 0
	s_lshr_b32 s28, s18, 8
	s_and_b32 s29, s18, 0xff
	s_lshl_b32 s28, s28, 5
	s_add_u32 s28, s28, s15
	s_lshl_b32 s28, s28, 8
	s_add_u32 s28, s28, s29
	s_waitcnt lgkmcnt(0)
	v_lshl_add_u64 v[4:5], s[12:13], 0, v[4:5]
	global_load_dwordx4 v[8:11], v[4:5], off nt
	v_lshl_add_u64 v[4:5], v[4:5], 0, s[26:27]
	global_load_dwordx4 v[12:15], v[4:5], off nt
	v_lshl_add_u64 v[4:5], v[4:5], 0, s[26:27]
	global_load_dwordx4 v[16:19], v[4:5], off nt
	v_lshl_add_u64 v[4:5], v[4:5], 0, s[26:27]
	global_load_dwordx4 v[20:23], v[4:5], off nt
	v_lshl_add_u64 v[4:5], v[4:5], 0, s[26:27]
	global_load_dwordx4 v[24:27], v[4:5], off nt
	v_lshl_add_u64 v[4:5], v[4:5], 0, s[26:27]
	global_load_dwordx4 v[28:31], v[4:5], off nt
	v_lshl_add_u64 v[4:5], v[4:5], 0, s[26:27]
	global_load_dwordx4 v[32:35], v[4:5], off nt
	v_lshl_add_u64 v[4:5], v[4:5], 0, s[26:27]
	global_load_dwordx4 v[36:39], v[4:5], off nt
	v_lshl_add_u32 v6, v3, 2, s28
	v_lshlrev_b32_e32 v6, 7, v6
	v_lshl_add_u32 v6, v2, 4, v6
	v_mov_b32_e32 v7, 0
	v_lshl_add_u64 v[6:7], s[20:21], 0, v[6:7]
	s_waitcnt vmcnt(0)
	v_cvt_pk_bf16_f32 v40, v8, v12
	v_cvt_pk_bf16_f32 v41, v16, v20
	v_cvt_pk_bf16_f32 v42, v24, v28
	v_cvt_pk_bf16_f32 v43, v32, v36
	global_store_dwordx4 v[6:7], v[40:43], off
	v_cvt_pk_bf16_f32 v44, v9, v13
	v_cvt_pk_bf16_f32 v45, v17, v21
	v_cvt_pk_bf16_f32 v46, v25, v29
	v_cvt_pk_bf16_f32 v47, v33, v37
	global_store_dwordx4 v[6:7], v[44:47], off offset:128
	v_cvt_pk_bf16_f32 v48, v10, v14
	v_cvt_pk_bf16_f32 v49, v18, v22
	v_cvt_pk_bf16_f32 v50, v26, v30
	v_cvt_pk_bf16_f32 v51, v34, v38
	global_store_dwordx4 v[6:7], v[48:51], off offset:256
	v_cvt_pk_bf16_f32 v52, v11, v15
	v_cvt_pk_bf16_f32 v53, v19, v23
	v_cvt_pk_bf16_f32 v54, v27, v31
	v_cvt_pk_bf16_f32 v55, v35, v39
	global_store_dwordx4 v[6:7], v[52:55], off offset:384
	s_waitcnt vmcnt(0)
.Lmy_cv2_done:
	s_branch .LBB0_356

.LBB0_434:
	s_or_b64 exec, exec, s[10:11]
	s_waitcnt vmcnt(0)
	s_branch .LBB0_435
.Lmy_cv3_entry:
	s_mov_b64 exec, -1
	s_cmpk_lg_i32 s3, 0x100
	s_cbranch_scc1 .Lmy_cv3_done
	v_readfirstlane_b32 s6, v0
	s_nop 0
	s_lshr_b32 s6, s6, 6
	s_mul_i32 s7, s2, 7
	s_add_i32 s6, s6, s7
	s_add_i32 s6, s6, 14079
	s_cmp_gt_u32 s6, 0x5fff
	s_cbranch_scc1 .Lmy_cv3_done
	v_and_b32_e32 v1, 63, v0
	v_readlane_b32 s10, v254, 2
	v_readlane_b32 s11, v254, 3
	s_sub_u32 s10, s10, 0xc8
	s_subb_u32 s11, s11, 0
	s_cmp_lt_u32 s6, 0x1600
	s_cbranch_scc1 .Lmy_cv3_g1
	s_cmp_lt_u32 s6, 0x2c00
	s_cbranch_scc1 .Lmy_cv3_u1
	s_cmp_lt_u32 s6, 0x3400
	s_cbranch_scc1 .Lmy_cv3_wo
	s_cmp_lt_u32 s6, 0x4a00
	s_cbranch_scc1 .Lmy_cv3_g2
	s_load_dwordx2 s[12:13], s[10:11], 0xa0
	s_sub_u32 s6, s6, 0x4a00
	s_movk_i32 s14, 0x80
	s_mov_b32 s20, 0x6a00000
	s_branch .Lmy_cv3_gu

.Lmy_cv4_entry:
	s_mov_b64 exec, -1
	s_cmpk_lg_i32 s3, 0x100
	s_cbranch_scc1 .Lmy_cv4_done
	v_readfirstlane_b32 s6, v0
	s_nop 0
	s_lshr_b32 s6, s6, 6
	s_mul_i32 s7, s2, 7
	s_add_i32 s6, s6, s7
	s_add_i32 s6, s6, 15871
	s_cmp_gt_u32 s6, 0x5fff
	s_cbranch_scc1 .Lmy_cv4_done
	v_and_b32_e32 v1, 63, v0
	v_readlane_b32 s10, v254, 2
	v_readlane_b32 s11, v254, 3
	s_sub_u32 s10, s10, 0xc8
	s_subb_u32 s11, s11, 0
	s_cmp_lt_u32 s6, 0x1600
	s_cbranch_scc1 .Lmy_cv4_g1
	s_cmp_lt_u32 s6, 0x2c00
	s_cbranch_scc1 .Lmy_cv4_u1
	s_cmp_lt_u32 s6, 0x3400
	s_cbranch_scc1 .Lmy_cv4_wo
	s_cmp_lt_u32 s6, 0x4a00
	s_cbranch_scc1 .Lmy_cv4_g2
	s_load_dwordx2 s[12:13], s[10:11], 0xa0
	s_sub_u32 s6, s6, 0x4a00
	s_movk_i32 s14, 0x80
	s_mov_b32 s20, 0x6a00000
	s_branch .Lmy_cv4_gu

.Lmy_cv5_entry:
	s_mov_b64 exec, -1
	s_cmpk_lg_i32 s3, 0x100
	s_cbranch_scc1 .Lmy_cv5_done
	v_readfirstlane_b32 s6, v0
	s_nop 0
	s_lshr_b32 s6, s6, 6
	s_mul_i32 s7, s2, 7
	s_add_i32 s6, s6, s7
	s_add_i32 s6, s6, 17663
	s_cmp_gt_u32 s6, 0x5fff
	s_cbranch_scc1 .Lmy_cv5_done
	v_and_b32_e32 v1, 63, v0
	v_readlane_b32 s10, v254, 2
	v_readlane_b32 s11, v254, 3
	s_sub_u32 s10, s10, 0xc8
	s_subb_u32 s11, s11, 0
	s_cmp_lt_u32 s6, 0x1600
	s_cbranch_scc1 .Lmy_cv5_g1
	s_cmp_lt_u32 s6, 0x2c00
	s_cbranch_scc1 .Lmy_cv5_u1
	s_cmp_lt_u32 s6, 0x3400
	s_cbranch_scc1 .Lmy_cv5_wo
	s_cmp_lt_u32 s6, 0x4a00
	s_cbranch_scc1 .Lmy_cv5_g2
	s_load_dwordx2 s[12:13], s[10:11], 0xa0
	s_sub_u32 s6, s6, 0x4a00
	s_movk_i32 s14, 0x80
	s_mov_b32 s20, 0x6a00000
	s_branch .Lmy_cv5_gu

.Lmy_cv6_entry:
	s_mov_b64 exec, -1
	s_cmpk_lg_i32 s3, 0x100
	s_cbranch_scc1 .Lmy_cv6_done
	v_readfirstlane_b32 s6, v0
	s_nop 0
	s_lshr_b32 s6, s6, 6
	s_mul_i32 s7, s2, 7
	s_add_i32 s6, s6, s7
	s_add_i32 s6, s6, 19455
	s_cmp_gt_u32 s6, 0x5fff
	s_cbranch_scc1 .Lmy_cv6_done
	v_and_b32_e32 v1, 63, v0
	v_readlane_b32 s10, v254, 2
	v_readlane_b32 s11, v254, 3
	s_sub_u32 s10, s10, 0xc8
	s_subb_u32 s11, s11, 0
	s_cmp_lt_u32 s6, 0x1600
	s_cbranch_scc1 .Lmy_cv6_g1
	s_cmp_lt_u32 s6, 0x2c00
	s_cbranch_scc1 .Lmy_cv6_u1
	s_cmp_lt_u32 s6, 0x3400
	s_cbranch_scc1 .Lmy_cv6_wo
	s_cmp_lt_u32 s6, 0x4a00
	s_cbranch_scc1 .Lmy_cv6_g2
	s_load_dwordx2 s[12:13], s[10:11], 0xa0
	s_sub_u32 s6, s6, 0x4a00
	s_movk_i32 s14, 0x80
	s_mov_b32 s20, 0x6a00000
	s_branch .Lmy_cv6_gu

.Lmy_cv7_entry:
	s_mov_b64 exec, -1
	s_cmpk_lg_i32 s3, 0x100
	s_cbranch_scc1 .Lmy_cv7_done
	v_readfirstlane_b32 s6, v0
	s_nop 0
	s_lshr_b32 s6, s6, 6
	s_mul_i32 s7, s2, 7
	s_add_i32 s6, s6, s7
	s_add_i32 s6, s6, 21247
	s_cmp_gt_u32 s6, 0x5fff
	s_cbranch_scc1 .Lmy_cv7_done
	v_and_b32_e32 v1, 63, v0
	v_readlane_b32 s10, v254, 2
	v_readlane_b32 s11, v254, 3
	s_sub_u32 s10, s10, 0xc8
	s_subb_u32 s11, s11, 0
	s_cmp_lt_u32 s6, 0x1600
	s_cbranch_scc1 .Lmy_cv7_g1
	s_cmp_lt_u32 s6, 0x2c00
	s_cbranch_scc1 .Lmy_cv7_u1
	s_cmp_lt_u32 s6, 0x3400
	s_cbranch_scc1 .Lmy_cv7_wo
	s_cmp_lt_u32 s6, 0x4a00
	s_cbranch_scc1 .Lmy_cv7_g2
	s_load_dwordx2 s[12:13], s[10:11], 0xa0
	s_sub_u32 s6, s6, 0x4a00
	s_movk_i32 s14, 0x80
	s_mov_b32 s20, 0x6a00000
	s_branch .Lmy_cv7_gu

.Lmy_cv8_entry:
	s_mov_b64 exec, -1
	s_cmpk_lg_i32 s3, 0x100
	s_cbranch_scc1 .Lmy_cv8_done
	v_readfirstlane_b32 s6, v0
	s_nop 0
	s_lshr_b32 s6, s6, 6
	s_mul_i32 s7, s2, 7
	s_add_i32 s6, s6, s7
	s_add_i32 s6, s6, 23039
	s_cmp_gt_u32 s6, 0x5fff
	s_cbranch_scc1 .Lmy_cv8_done
	v_and_b32_e32 v1, 63, v0
	v_readlane_b32 s10, v254, 2
	v_readlane_b32 s11, v254, 3
	s_sub_u32 s10, s10, 0xc8
	s_subb_u32 s11, s11, 0
	s_cmp_lt_u32 s6, 0x1600
	s_cbranch_scc1 .Lmy_cv8_g1
	s_cmp_lt_u32 s6, 0x2c00
	s_cbranch_scc1 .Lmy_cv8_u1
	s_cmp_lt_u32 s6, 0x3400
	s_cbranch_scc1 .Lmy_cv8_wo
	s_cmp_lt_u32 s6, 0x4a00
	s_cbranch_scc1 .Lmy_cv8_g2
	s_load_dwordx2 s[12:13], s[10:11], 0xa0
	s_sub_u32 s6, s6, 0x4a00
	s_movk_i32 s14, 0x80
	s_mov_b32 s20, 0x6a00000
	s_branch .Lmy_cv8_gu
